# pipelined residual epilogue also in attn-out and hyena-out GEMM sites
# speedup vs baseline: 1.0152x; 1.0076x over previous
; __device__ __forceinline__ unsigned cvtpk(float lo, float hi) { f32x2 v = {lo, hi}; bf16x2_t b = __builtin_convertvector(v, bf16x2_t); return __builtin_bit_cast(unsigned, b); }
;     __device__ __forceinline__ void operator()(const f32x4 (&acc)[2][2][4][2], const pg8::Unit& u, int wr, int wc, int fr, int fq) const {
;     ...
;                 const int grow = row_base + u.pm * 256 + ai * 128 + wr * 64 + m * 16 + fr;
;                 const bool ok = grow < MREAL;
;                 float ss = 0.f;
;                 if (ok) {
;                     const float* src; float* dst;
;                     if (grow < ROWS_P) { src = srcA + (size_t)grow * DM; dst = dstMain + (size_t)grow * DM; }
;                     else if (grow < ROWS_MAIN) { src = srcB + (size_t)(grow - ROWS_P) * DM; dst = dstMain + (size_t)grow * DM; }
;                     else { const int mr = grow - ROWS_MAIN; src = srcM + (size_t)(mr & meta_mask) * DM; dst = dstM + (size_t)mr * DM; }
; #pragma unroll
;                     for (int bj = 0; bj < 2; ++bj) {
;                         const int col0 = u.pn * 256 + bj * 128 + wc * 32 + 8 * fq;
;                         const f32x4 h0 = *(const f32x4*)(src + col0) + acc[ai][bj][m][0];
;                         const f32x4 h1 = *(const f32x4*)(src + col0 + 4) + acc[ai][bj][m][1];
;                         *(f32x4*)(dst + col0) = h0; *(f32x4*)(dst + col0 + 4) = h1;
;                         if (P) { u32x4 w; w.x = cvtpk(h0[0], h0[1]); w.y = cvtpk(h0[2], h0[3]); w.z = cvtpk(h1[0], h1[1]); w.w = cvtpk(h1[2], h1[3]);
;                             *(u32x4*)(P + (size_t)grow * DM + col0) = w; }
;                         ss += (h0[0] * h0[0] + h0[1] * h0[1]) + (h0[2] * h0[2] + h0[3] * h0[3]) + (h1[0] * h1[0] + h1[1] * h1[1]) + (h1[2] * h1[2] + h1[3] * h1[3]);
;                     }
;                 }
;                 ss += __shfl_xor(ss, 16); ss += __shfl_xor(ss, 32);
;                 if (ok && fq == 0 && rowss_next) atomicAdd(rowss_next + grow, (u64)(ss * SS_SCALE));
.LBB0_798:
	s_lshl_b32 vcc_lo, s42, 8
	s_cmp_lt_u32 vcc_lo, 0x18000
	s_cbranch_scc0 .Lepi_old_ao
	s_cmp_lg_u64 s[28:29], 0
	s_cbranch_scc0 .Lepi_old_ao
	s_cmp_lg_u64 s[30:31], 0
	s_cbranch_scc0 .Lepi_old_ao
	s_lshl_b32 vcc_hi, s8, 10
	s_lshl_b32 s8, vcc_lo, 3
	s_add_u32 s8, s16, s8
	s_addc_u32 s9, s17, 0
	s_lshl_b32 s6, vcc_lo, 12
	s_add_u32 vcc_hi, vcc_hi, s6
	s_add_u32 s44, s12, vcc_hi
	s_addc_u32 s45, s13, 0
	s_lshr_b32 s6, vcc_hi, 1
	s_add_u32 s6, s10, s6
	s_addc_u32 s7, s11, 0
	s_cmp_lt_u32 vcc_lo, 0x8000
	s_cselect_b32 s42, s24, s22
	s_cselect_b32 s43, s25, s23
	s_cselect_b32 vcc_lo, 0, 0x8000000
	s_sub_u32 vcc_hi, vcc_hi, vcc_lo
	s_add_u32 s42, s42, vcc_hi
	s_addc_u32 s43, s43, 0
	v_lshlrev_b32_e32 v150, 12, v164
	v_lshl_add_u32 v150, v166, 2, v150
	v_lshrrev_b32_e32 v151, 1, v150
	v_lshlrev_b32_e32 v162, 3, v164
	global_load_dwordx4 v[168:171], v150, s[42:43]
	global_load_dwordx4 v[172:175], v150, s[42:43] offset:16
	global_load_dwordx4 v[176:179], v150, s[42:43] offset:512
	global_load_dwordx4 v[180:183], v150, s[42:43] offset:528
	s_add_u32 s42, s42, 0x10000
	s_addc_u32 s43, s43, 0
	global_load_dwordx4 v[184:187], v150, s[42:43]
	global_load_dwordx4 v[188:191], v150, s[42:43] offset:16
	global_load_dwordx4 v[192:195], v150, s[42:43] offset:512
	global_load_dwordx4 v[196:199], v150, s[42:43] offset:528
	s_add_u32 s42, s42, 0x10000
	s_addc_u32 s43, s43, 0
	global_load_dwordx4 v[216:219], v150, s[42:43]
	global_load_dwordx4 v[220:223], v150, s[42:43] offset:16
	global_load_dwordx4 v[224:227], v150, s[42:43] offset:512
	global_load_dwordx4 v[228:231], v150, s[42:43] offset:528
	s_add_u32 s42, s42, 0x10000
	s_addc_u32 s43, s43, 0
	global_load_dwordx4 v[142:145], v150, s[42:43]
	global_load_dwordx4 v[146:149], v150, s[42:43] offset:16
	global_load_dwordx4 v[158:161], v150, s[42:43] offset:512
	global_load_dwordx4 v[204:207], v150, s[42:43] offset:528
	s_add_u32 s42, s42, 0x50000
	s_addc_u32 s43, s43, 0
	s_waitcnt vmcnt(12)
	v_pk_add_f32 v[126:127], v[126:127], v[168:169]
	v_pk_add_f32 v[128:129], v[128:129], v[170:171]
	v_pk_add_f32 v[122:123], v[122:123], v[172:173]
	v_pk_add_f32 v[124:125], v[124:125], v[174:175]
	v_pk_add_f32 v[118:119], v[118:119], v[176:177]
	v_pk_add_f32 v[120:121], v[120:121], v[178:179]
	v_pk_add_f32 v[114:115], v[114:115], v[180:181]
	v_pk_add_f32 v[116:117], v[116:117], v[182:183]
	global_store_dwordx4 v150, v[126:129], s[44:45]
	global_store_dwordx4 v150, v[122:125], s[44:45] offset:16
	global_store_dwordx4 v150, v[118:121], s[44:45] offset:512
	global_store_dwordx4 v150, v[114:117], s[44:45] offset:528
	v_cvt_pk_bf16_f32 v168, v126, v127
	v_cvt_pk_bf16_f32 v169, v128, v129
	v_cvt_pk_bf16_f32 v170, v122, v123
	v_cvt_pk_bf16_f32 v171, v124, v125
	v_cvt_pk_bf16_f32 v172, v118, v119
	v_cvt_pk_bf16_f32 v173, v120, v121
	v_cvt_pk_bf16_f32 v174, v114, v115
	v_cvt_pk_bf16_f32 v175, v116, v117
	global_store_dwordx4 v151, v[168:171], s[6:7]
	global_store_dwordx4 v151, v[172:175], s[6:7] offset:256
	v_mul_f32_e32 v163, v126, v126
	v_mul_f32_e32 v200, v127, v127
	v_fmac_f32_e32 v163, v128, v128
	v_fmac_f32_e32 v200, v129, v129
	v_fmac_f32_e32 v163, v122, v122
	v_fmac_f32_e32 v200, v123, v123
	v_fmac_f32_e32 v163, v124, v124
	v_fmac_f32_e32 v200, v125, v125
	v_fmac_f32_e32 v163, v118, v118
	v_fmac_f32_e32 v200, v119, v119
	v_fmac_f32_e32 v163, v120, v120
	v_fmac_f32_e32 v200, v121, v121
	v_fmac_f32_e32 v163, v114, v114
	v_fmac_f32_e32 v200, v115, v115
	v_fmac_f32_e32 v163, v116, v116
	v_fmac_f32_e32 v200, v117, v117
	v_add_f32_e32 v114, v163, v200
	s_add_u32 s44, s44, 0x10000
	s_addc_u32 s45, s45, 0
	s_add_u32 s6, s6, 0x8000
	s_addc_u32 s7, s7, 0
	global_load_dwordx4 v[168:171], v150, s[42:43]
	global_load_dwordx4 v[172:175], v150, s[42:43] offset:16
	global_load_dwordx4 v[176:179], v150, s[42:43] offset:512
	global_load_dwordx4 v[180:183], v150, s[42:43] offset:528
	s_add_u32 s42, s42, 0x10000
	s_addc_u32 s43, s43, 0
	s_waitcnt vmcnt(18)
	v_pk_add_f32 v[110:111], v[110:111], v[184:185]
	v_pk_add_f32 v[112:113], v[112:113], v[186:187]
	v_pk_add_f32 v[106:107], v[106:107], v[188:189]
	v_pk_add_f32 v[108:109], v[108:109], v[190:191]
	v_pk_add_f32 v[102:103], v[102:103], v[192:193]
	v_pk_add_f32 v[104:105], v[104:105], v[194:195]
	v_pk_add_f32 v[98:99], v[98:99], v[196:197]
	v_pk_add_f32 v[100:101], v[100:101], v[198:199]
	global_store_dwordx4 v150, v[110:113], s[44:45]
	global_store_dwordx4 v150, v[106:109], s[44:45] offset:16
	global_store_dwordx4 v150, v[102:105], s[44:45] offset:512
	global_store_dwordx4 v150, v[98:101], s[44:45] offset:528
	v_cvt_pk_bf16_f32 v184, v110, v111
	v_cvt_pk_bf16_f32 v185, v112, v113
	v_cvt_pk_bf16_f32 v186, v106, v107
	v_cvt_pk_bf16_f32 v187, v108, v109
	v_cvt_pk_bf16_f32 v188, v102, v103
	v_cvt_pk_bf16_f32 v189, v104, v105
	v_cvt_pk_bf16_f32 v190, v98, v99
	v_cvt_pk_bf16_f32 v191, v100, v101
	global_store_dwordx4 v151, v[184:187], s[6:7]
	global_store_dwordx4 v151, v[188:191], s[6:7] offset:256
	v_mul_f32_e32 v163, v110, v110
	v_mul_f32_e32 v200, v111, v111
	v_fmac_f32_e32 v163, v112, v112
	v_fmac_f32_e32 v200, v113, v113
	v_fmac_f32_e32 v163, v106, v106
	v_fmac_f32_e32 v200, v107, v107
	v_fmac_f32_e32 v163, v108, v108
	v_fmac_f32_e32 v200, v109, v109
	v_fmac_f32_e32 v163, v102, v102
	v_fmac_f32_e32 v200, v103, v103
	v_fmac_f32_e32 v163, v104, v104
	v_fmac_f32_e32 v200, v105, v105
	v_fmac_f32_e32 v163, v98, v98
	v_fmac_f32_e32 v200, v99, v99
	v_fmac_f32_e32 v163, v100, v100
	v_fmac_f32_e32 v200, v101, v101
	v_add_f32_e32 v98, v163, v200
	s_add_u32 s44, s44, 0x10000
	s_addc_u32 s45, s45, 0
	s_add_u32 s6, s6, 0x8000
	s_addc_u32 s7, s7, 0
	global_load_dwordx4 v[184:187], v150, s[42:43]
	global_load_dwordx4 v[188:191], v150, s[42:43] offset:16
	global_load_dwordx4 v[192:195], v150, s[42:43] offset:512
	global_load_dwordx4 v[196:199], v150, s[42:43] offset:528
	s_add_u32 s42, s42, 0x10000
	s_addc_u32 s43, s43, 0
	s_waitcnt vmcnt(24)
; __device__ __forceinline__ unsigned cvtpk(float lo, float hi) { f32x2 v = {lo, hi}; bf16x2_t b = __builtin_convertvector(v, bf16x2_t); return __builtin_bit_cast(unsigned, b); }
;     __device__ __forceinline__ void operator()(const f32x4 (&acc)[2][2][4][2], const pg8::Unit& u, int wr, int wc, int fr, int fq) const {
;     ...
;                 const int grow = row_base + u.pm * 256 + ai * 128 + wr * 64 + m * 16 + fr;
;                 const bool ok = grow < MREAL;
;                 float ss = 0.f;
;                 if (ok) {
;                     const float* src; float* dst;
;                     if (grow < ROWS_P) { src = srcA + (size_t)grow * DM; dst = dstMain + (size_t)grow * DM; }
;                     else if (grow < ROWS_MAIN) { src = srcB + (size_t)(grow - ROWS_P) * DM; dst = dstMain + (size_t)grow * DM; }
;                     else { const int mr = grow - ROWS_MAIN; src = srcM + (size_t)(mr & meta_mask) * DM; dst = dstM + (size_t)mr * DM; }
; #pragma unroll
;                     for (int bj = 0; bj < 2; ++bj) {
;                         const int col0 = u.pn * 256 + bj * 128 + wc * 32 + 8 * fq;
;                         const f32x4 h0 = *(const f32x4*)(src + col0) + acc[ai][bj][m][0];
;                         const f32x4 h1 = *(const f32x4*)(src + col0 + 4) + acc[ai][bj][m][1];
;                         *(f32x4*)(dst + col0) = h0; *(f32x4*)(dst + col0 + 4) = h1;
;                         if (P) { u32x4 w; w.x = cvtpk(h0[0], h0[1]); w.y = cvtpk(h0[2], h0[3]); w.z = cvtpk(h1[0], h1[1]); w.w = cvtpk(h1[2], h1[3]);
;                             *(u32x4*)(P + (size_t)grow * DM + col0) = w; }
;                         ss += (h0[0] * h0[0] + h0[1] * h0[1]) + (h0[2] * h0[2] + h0[3] * h0[3]) + (h1[0] * h1[0] + h1[1] * h1[1]) + (h1[2] * h1[2] + h1[3] * h1[3]);
;                     }
;                 }
;                 ss += __shfl_xor(ss, 16); ss += __shfl_xor(ss, 32);
;                 if (ok && fq == 0 && rowss_next) atomicAdd(rowss_next + grow, (u64)(ss * SS_SCALE));
	v_pk_add_f32 v[94:95], v[94:95], v[216:217]
	v_pk_add_f32 v[96:97], v[96:97], v[218:219]
	v_pk_add_f32 v[90:91], v[90:91], v[220:221]
	v_pk_add_f32 v[92:93], v[92:93], v[222:223]
	v_pk_add_f32 v[86:87], v[86:87], v[224:225]
	v_pk_add_f32 v[88:89], v[88:89], v[226:227]
	v_pk_add_f32 v[82:83], v[82:83], v[228:229]
	v_pk_add_f32 v[84:85], v[84:85], v[230:231]
	global_store_dwordx4 v150, v[94:97], s[44:45]
	global_store_dwordx4 v150, v[90:93], s[44:45] offset:16
	global_store_dwordx4 v150, v[86:89], s[44:45] offset:512
	global_store_dwordx4 v150, v[82:85], s[44:45] offset:528
	v_cvt_pk_bf16_f32 v216, v94, v95
	v_cvt_pk_bf16_f32 v217, v96, v97
	v_cvt_pk_bf16_f32 v218, v90, v91
	v_cvt_pk_bf16_f32 v219, v92, v93
	v_cvt_pk_bf16_f32 v220, v86, v87
	v_cvt_pk_bf16_f32 v221, v88, v89
	v_cvt_pk_bf16_f32 v222, v82, v83
	v_cvt_pk_bf16_f32 v223, v84, v85
	global_store_dwordx4 v151, v[216:219], s[6:7]
	global_store_dwordx4 v151, v[220:223], s[6:7] offset:256
	v_mul_f32_e32 v163, v94, v94
	v_mul_f32_e32 v200, v95, v95
	v_fmac_f32_e32 v163, v96, v96
	v_fmac_f32_e32 v200, v97, v97
	v_fmac_f32_e32 v163, v90, v90
	v_fmac_f32_e32 v200, v91, v91
	v_fmac_f32_e32 v163, v92, v92
	v_fmac_f32_e32 v200, v93, v93
	v_fmac_f32_e32 v163, v86, v86
	v_fmac_f32_e32 v200, v87, v87
	v_fmac_f32_e32 v163, v88, v88
	v_fmac_f32_e32 v200, v89, v89
	v_fmac_f32_e32 v163, v82, v82
	v_fmac_f32_e32 v200, v83, v83
	v_fmac_f32_e32 v163, v84, v84
	v_fmac_f32_e32 v200, v85, v85
	v_add_f32_e32 v82, v163, v200
	s_add_u32 s44, s44, 0x10000
	s_addc_u32 s45, s45, 0
	s_add_u32 s6, s6, 0x8000
	s_addc_u32 s7, s7, 0
	global_load_dwordx4 v[216:219], v150, s[42:43]
	global_load_dwordx4 v[220:223], v150, s[42:43] offset:16
	global_load_dwordx4 v[224:227], v150, s[42:43] offset:512
	global_load_dwordx4 v[228:231], v150, s[42:43] offset:528
	s_add_u32 s42, s42, 0x10000
	s_addc_u32 s43, s43, 0
	s_waitcnt vmcnt(30)
	v_pk_add_f32 v[78:79], v[78:79], v[142:143]
	v_pk_add_f32 v[80:81], v[80:81], v[144:145]
	v_pk_add_f32 v[74:75], v[74:75], v[146:147]
	v_pk_add_f32 v[76:77], v[76:77], v[148:149]
	v_pk_add_f32 v[70:71], v[70:71], v[158:159]
	v_pk_add_f32 v[72:73], v[72:73], v[160:161]
	v_pk_add_f32 v[66:67], v[66:67], v[204:205]
	v_pk_add_f32 v[68:69], v[68:69], v[206:207]
	global_store_dwordx4 v150, v[78:81], s[44:45]
	global_store_dwordx4 v150, v[74:77], s[44:45] offset:16
	global_store_dwordx4 v150, v[70:73], s[44:45] offset:512
	global_store_dwordx4 v150, v[66:69], s[44:45] offset:528
	v_cvt_pk_bf16_f32 v142, v78, v79
	v_cvt_pk_bf16_f32 v143, v80, v81
	v_cvt_pk_bf16_f32 v144, v74, v75
	v_cvt_pk_bf16_f32 v145, v76, v77
	v_cvt_pk_bf16_f32 v146, v70, v71
	v_cvt_pk_bf16_f32 v147, v72, v73
	v_cvt_pk_bf16_f32 v148, v66, v67
	v_cvt_pk_bf16_f32 v149, v68, v69
	global_store_dwordx4 v151, v[142:145], s[6:7]
	global_store_dwordx4 v151, v[146:149], s[6:7] offset:256
	v_mul_f32_e32 v163, v78, v78
	v_mul_f32_e32 v200, v79, v79
	v_fmac_f32_e32 v163, v80, v80
	v_fmac_f32_e32 v200, v81, v81
	v_fmac_f32_e32 v163, v74, v74
	v_fmac_f32_e32 v200, v75, v75
	v_fmac_f32_e32 v163, v76, v76
	v_fmac_f32_e32 v200, v77, v77
	v_fmac_f32_e32 v163, v70, v70
	v_fmac_f32_e32 v200, v71, v71
	v_fmac_f32_e32 v163, v72, v72
	v_fmac_f32_e32 v200, v73, v73
	v_fmac_f32_e32 v163, v66, v66
	v_fmac_f32_e32 v200, v67, v67
	v_fmac_f32_e32 v163, v68, v68
	v_fmac_f32_e32 v200, v69, v69
	v_add_f32_e32 v66, v163, v200
	s_add_u32 s44, s44, 0x50000
	s_addc_u32 s45, s45, 0
	s_add_u32 s6, s6, 0x28000
	s_addc_u32 s7, s7, 0
	global_load_dwordx4 v[142:145], v150, s[42:43]
	global_load_dwordx4 v[146:149], v150, s[42:43] offset:16
	global_load_dwordx4 v[158:161], v150, s[42:43] offset:512
	global_load_dwordx4 v[204:207], v150, s[42:43] offset:528
	s_waitcnt vmcnt(30)
	v_pk_add_f32 v[62:63], v[62:63], v[168:169]
	v_pk_add_f32 v[64:65], v[64:65], v[170:171]
	v_pk_add_f32 v[58:59], v[58:59], v[172:173]
	v_pk_add_f32 v[60:61], v[60:61], v[174:175]
	v_pk_add_f32 v[54:55], v[54:55], v[176:177]
	v_pk_add_f32 v[56:57], v[56:57], v[178:179]
	v_pk_add_f32 v[50:51], v[50:51], v[180:181]
	v_pk_add_f32 v[52:53], v[52:53], v[182:183]
	global_store_dwordx4 v150, v[62:65], s[44:45]
	global_store_dwordx4 v150, v[58:61], s[44:45] offset:16
	global_store_dwordx4 v150, v[54:57], s[44:45] offset:512
	global_store_dwordx4 v150, v[50:53], s[44:45] offset:528
	v_cvt_pk_bf16_f32 v168, v62, v63
	v_cvt_pk_bf16_f32 v169, v64, v65
	v_cvt_pk_bf16_f32 v170, v58, v59
	v_cvt_pk_bf16_f32 v171, v60, v61
	v_cvt_pk_bf16_f32 v172, v54, v55
	v_cvt_pk_bf16_f32 v173, v56, v57
	v_cvt_pk_bf16_f32 v174, v50, v51
	v_cvt_pk_bf16_f32 v175, v52, v53
	global_store_dwordx4 v151, v[168:171], s[6:7]
	global_store_dwordx4 v151, v[172:175], s[6:7] offset:256
	v_mul_f32_e32 v163, v62, v62
	v_mul_f32_e32 v200, v63, v63
	v_fmac_f32_e32 v163, v64, v64
	v_fmac_f32_e32 v200, v65, v65
	v_fmac_f32_e32 v163, v58, v58
	v_fmac_f32_e32 v200, v59, v59
	v_fmac_f32_e32 v163, v60, v60
	v_fmac_f32_e32 v200, v61, v61
	v_fmac_f32_e32 v163, v54, v54
	v_fmac_f32_e32 v200, v55, v55
	v_fmac_f32_e32 v163, v56, v56
	v_fmac_f32_e32 v200, v57, v57
	v_fmac_f32_e32 v163, v50, v50
	v_fmac_f32_e32 v200, v51, v51
	v_fmac_f32_e32 v163, v52, v52
	v_fmac_f32_e32 v200, v53, v53
	v_add_f32_e32 v50, v163, v200
	s_add_u32 s44, s44, 0x10000
	s_addc_u32 s45, s45, 0
	s_add_u32 s6, s6, 0x8000
	s_addc_u32 s7, s7, 0
	s_waitcnt vmcnt(26)
; __device__ __forceinline__ unsigned cvtpk(float lo, float hi) { f32x2 v = {lo, hi}; bf16x2_t b = __builtin_convertvector(v, bf16x2_t); return __builtin_bit_cast(unsigned, b); }
;     __device__ __forceinline__ void operator()(const f32x4 (&acc)[2][2][4][2], const pg8::Unit& u, int wr, int wc, int fr, int fq) const {
;     ...
;                 const int grow = row_base + u.pm * 256 + ai * 128 + wr * 64 + m * 16 + fr;
;                 const bool ok = grow < MREAL;
;                 float ss = 0.f;
;                 if (ok) {
;                     const float* src; float* dst;
;                     if (grow < ROWS_P) { src = srcA + (size_t)grow * DM; dst = dstMain + (size_t)grow * DM; }
;                     else if (grow < ROWS_MAIN) { src = srcB + (size_t)(grow - ROWS_P) * DM; dst = dstMain + (size_t)grow * DM; }
;                     else { const int mr = grow - ROWS_MAIN; src = srcM + (size_t)(mr & meta_mask) * DM; dst = dstM + (size_t)mr * DM; }
; #pragma unroll
;                     for (int bj = 0; bj < 2; ++bj) {
;                         const int col0 = u.pn * 256 + bj * 128 + wc * 32 + 8 * fq;
;                         const f32x4 h0 = *(const f32x4*)(src + col0) + acc[ai][bj][m][0];
;                         const f32x4 h1 = *(const f32x4*)(src + col0 + 4) + acc[ai][bj][m][1];
;                         *(f32x4*)(dst + col0) = h0; *(f32x4*)(dst + col0 + 4) = h1;
;                         if (P) { u32x4 w; w.x = cvtpk(h0[0], h0[1]); w.y = cvtpk(h0[2], h0[3]); w.z = cvtpk(h1[0], h1[1]); w.w = cvtpk(h1[2], h1[3]);
;                             *(u32x4*)(P + (size_t)grow * DM + col0) = w; }
;                         ss += (h0[0] * h0[0] + h0[1] * h0[1]) + (h0[2] * h0[2] + h0[3] * h0[3]) + (h1[0] * h1[0] + h1[1] * h1[1]) + (h1[2] * h1[2] + h1[3] * h1[3]);
;                     }
;                 }
;                 ss += __shfl_xor(ss, 16); ss += __shfl_xor(ss, 32);
;                 if (ok && fq == 0 && rowss_next) atomicAdd(rowss_next + grow, (u64)(ss * SS_SCALE));
	v_pk_add_f32 v[46:47], v[46:47], v[184:185]
	v_pk_add_f32 v[48:49], v[48:49], v[186:187]
	v_pk_add_f32 v[42:43], v[42:43], v[188:189]
	v_pk_add_f32 v[44:45], v[44:45], v[190:191]
	v_pk_add_f32 v[38:39], v[38:39], v[192:193]
	v_pk_add_f32 v[40:41], v[40:41], v[194:195]
	v_pk_add_f32 v[34:35], v[34:35], v[196:197]
	v_pk_add_f32 v[36:37], v[36:37], v[198:199]
	global_store_dwordx4 v150, v[46:49], s[44:45]
	global_store_dwordx4 v150, v[42:45], s[44:45] offset:16
	global_store_dwordx4 v150, v[38:41], s[44:45] offset:512
	global_store_dwordx4 v150, v[34:37], s[44:45] offset:528
	v_cvt_pk_bf16_f32 v184, v46, v47
	v_cvt_pk_bf16_f32 v185, v48, v49
	v_cvt_pk_bf16_f32 v186, v42, v43
	v_cvt_pk_bf16_f32 v187, v44, v45
	v_cvt_pk_bf16_f32 v188, v38, v39
	v_cvt_pk_bf16_f32 v189, v40, v41
	v_cvt_pk_bf16_f32 v190, v34, v35
	v_cvt_pk_bf16_f32 v191, v36, v37
	global_store_dwordx4 v151, v[184:187], s[6:7]
	global_store_dwordx4 v151, v[188:191], s[6:7] offset:256
	v_mul_f32_e32 v163, v46, v46
	v_mul_f32_e32 v200, v47, v47
	v_fmac_f32_e32 v163, v48, v48
	v_fmac_f32_e32 v200, v49, v49
	v_fmac_f32_e32 v163, v42, v42
	v_fmac_f32_e32 v200, v43, v43
	v_fmac_f32_e32 v163, v44, v44
	v_fmac_f32_e32 v200, v45, v45
	v_fmac_f32_e32 v163, v38, v38
	v_fmac_f32_e32 v200, v39, v39
	v_fmac_f32_e32 v163, v40, v40
	v_fmac_f32_e32 v200, v41, v41
	v_fmac_f32_e32 v163, v34, v34
	v_fmac_f32_e32 v200, v35, v35
	v_fmac_f32_e32 v163, v36, v36
	v_fmac_f32_e32 v200, v37, v37
	v_add_f32_e32 v34, v163, v200
	s_add_u32 s44, s44, 0x10000
	s_addc_u32 s45, s45, 0
	s_add_u32 s6, s6, 0x8000
	s_addc_u32 s7, s7, 0
	s_waitcnt vmcnt(22)
	v_pk_add_f32 v[28:29], v[28:29], v[216:217]
	v_pk_add_f32 v[30:31], v[30:31], v[218:219]
	v_pk_add_f32 v[24:25], v[24:25], v[220:221]
	v_pk_add_f32 v[26:27], v[26:27], v[222:223]
	v_pk_add_f32 v[20:21], v[20:21], v[224:225]
	v_pk_add_f32 v[22:23], v[22:23], v[226:227]
	v_pk_add_f32 v[16:17], v[16:17], v[228:229]
	v_pk_add_f32 v[18:19], v[18:19], v[230:231]
	global_store_dwordx4 v150, v[28:31], s[44:45]
	global_store_dwordx4 v150, v[24:27], s[44:45] offset:16
	global_store_dwordx4 v150, v[20:23], s[44:45] offset:512
	global_store_dwordx4 v150, v[16:19], s[44:45] offset:528
	v_cvt_pk_bf16_f32 v216, v28, v29
	v_cvt_pk_bf16_f32 v217, v30, v31
	v_cvt_pk_bf16_f32 v218, v24, v25
	v_cvt_pk_bf16_f32 v219, v26, v27
	v_cvt_pk_bf16_f32 v220, v20, v21
	v_cvt_pk_bf16_f32 v221, v22, v23
	v_cvt_pk_bf16_f32 v222, v16, v17
	v_cvt_pk_bf16_f32 v223, v18, v19
	global_store_dwordx4 v151, v[216:219], s[6:7]
	global_store_dwordx4 v151, v[220:223], s[6:7] offset:256
	v_mul_f32_e32 v163, v28, v28
	v_mul_f32_e32 v200, v29, v29
	v_fmac_f32_e32 v163, v30, v30
	v_fmac_f32_e32 v200, v31, v31
	v_fmac_f32_e32 v163, v24, v24
	v_fmac_f32_e32 v200, v25, v25
	v_fmac_f32_e32 v163, v26, v26
	v_fmac_f32_e32 v200, v27, v27
	v_fmac_f32_e32 v163, v20, v20
	v_fmac_f32_e32 v200, v21, v21
	v_fmac_f32_e32 v163, v22, v22
	v_fmac_f32_e32 v200, v23, v23
	v_fmac_f32_e32 v163, v16, v16
	v_fmac_f32_e32 v200, v17, v17
	v_fmac_f32_e32 v163, v18, v18
	v_fmac_f32_e32 v200, v19, v19
	v_add_f32_e32 v16, v163, v200
	s_add_u32 s44, s44, 0x10000
	s_addc_u32 s45, s45, 0
	s_add_u32 s6, s6, 0x8000
	s_addc_u32 s7, s7, 0
	s_waitcnt vmcnt(18)
;     __device__ __forceinline__ void operator()(const f32x4 (&acc)[2][2][4][2], const pg8::Unit& u, int wr, int wc, int fr, int fq) const {
;     ...
;                         ss += (h0[0] * h0[0] + h0[1] * h0[1]) + (h0[2] * h0[2] + h0[3] * h0[3]) + (h1[0] * h1[0] + h1[1] * h1[1]) + (h1[2] * h1[2] + h1[3] * h1[3]);
;                     }
;                 }
;                 ss += __shfl_xor(ss, 16); ss += __shfl_xor(ss, 32);
;                 if (ok && fq == 0 && rowss_next) atomicAdd(rowss_next + grow, (u64)(ss * SS_SCALE));
	v_pk_add_f32 v[12:13], v[12:13], v[142:143]
	v_pk_add_f32 v[14:15], v[14:15], v[144:145]
	v_pk_add_f32 v[8:9], v[8:9], v[146:147]
	v_pk_add_f32 v[10:11], v[10:11], v[148:149]
	v_pk_add_f32 v[4:5], v[4:5], v[158:159]
	v_pk_add_f32 v[6:7], v[6:7], v[160:161]
	v_pk_add_f32 v[0:1], v[0:1], v[204:205]
	v_pk_add_f32 v[2:3], v[2:3], v[206:207]
	global_store_dwordx4 v150, v[12:15], s[44:45]
	global_store_dwordx4 v150, v[8:11], s[44:45] offset:16
	global_store_dwordx4 v150, v[4:7], s[44:45] offset:512
	global_store_dwordx4 v150, v[0:3], s[44:45] offset:528
	v_cvt_pk_bf16_f32 v142, v12, v13
	v_cvt_pk_bf16_f32 v143, v14, v15
	v_cvt_pk_bf16_f32 v144, v8, v9
	v_cvt_pk_bf16_f32 v145, v10, v11
	v_cvt_pk_bf16_f32 v146, v4, v5
	v_cvt_pk_bf16_f32 v147, v6, v7
	v_cvt_pk_bf16_f32 v148, v0, v1
	v_cvt_pk_bf16_f32 v149, v2, v3
	global_store_dwordx4 v151, v[142:145], s[6:7]
	global_store_dwordx4 v151, v[146:149], s[6:7] offset:256
	v_mul_f32_e32 v163, v12, v12
	v_mul_f32_e32 v200, v13, v13
	v_fmac_f32_e32 v163, v14, v14
	v_fmac_f32_e32 v200, v15, v15
	v_fmac_f32_e32 v163, v8, v8
	v_fmac_f32_e32 v200, v9, v9
	v_fmac_f32_e32 v163, v10, v10
	v_fmac_f32_e32 v200, v11, v11
	v_fmac_f32_e32 v163, v4, v4
	v_fmac_f32_e32 v200, v5, v5
	v_fmac_f32_e32 v163, v6, v6
	v_fmac_f32_e32 v200, v7, v7
	v_fmac_f32_e32 v163, v0, v0
	v_fmac_f32_e32 v200, v1, v1
	v_fmac_f32_e32 v163, v2, v2
	v_fmac_f32_e32 v200, v3, v3
	v_add_f32_e32 v0, v163, v200
	v_mbcnt_lo_u32_b32 v201, -1, 0
	v_mbcnt_hi_u32_b32 v201, -1, v201
	v_xor_b32_e32 v208, 16, v201
	v_xor_b32_e32 v209, 32, v201
	v_lshlrev_b32_e32 v208, 2, v208
	v_lshlrev_b32_e32 v209, 2, v209
	ds_bpermute_b32 v115, v208, v114
	ds_bpermute_b32 v99, v208, v98
	ds_bpermute_b32 v83, v208, v82
	ds_bpermute_b32 v67, v208, v66
	ds_bpermute_b32 v51, v208, v50
	ds_bpermute_b32 v35, v208, v34
	ds_bpermute_b32 v17, v208, v16
	ds_bpermute_b32 v1, v208, v0
	s_waitcnt lgkmcnt(0)
	v_add_f32_e32 v114, v114, v115
	v_add_f32_e32 v98, v98, v99
	v_add_f32_e32 v82, v82, v83
	v_add_f32_e32 v66, v66, v67
	v_add_f32_e32 v50, v50, v51
	v_add_f32_e32 v34, v34, v35
	v_add_f32_e32 v16, v16, v17
	v_add_f32_e32 v0, v0, v1
	ds_bpermute_b32 v115, v209, v114
	ds_bpermute_b32 v99, v209, v98
	ds_bpermute_b32 v83, v209, v82
	ds_bpermute_b32 v67, v209, v66
	ds_bpermute_b32 v51, v209, v50
	ds_bpermute_b32 v35, v209, v34
	ds_bpermute_b32 v17, v209, v16
	ds_bpermute_b32 v1, v209, v0
	s_waitcnt lgkmcnt(0)
	v_add_f32_e32 v114, v114, v115
	v_add_f32_e32 v98, v98, v99
	v_add_f32_e32 v82, v82, v83
	v_add_f32_e32 v66, v66, v67
	v_add_f32_e32 v50, v50, v51
	v_add_f32_e32 v34, v34, v35
	v_add_f32_e32 v16, v16, v17
	v_add_f32_e32 v0, v0, v1
	s_and_saveexec_b64 s[42:43], s[2:3]
	v_mul_f32_e32 v114, 0x49800000, v114
	v_trunc_f32_e32 v114, v114
	v_mul_f32_e32 v115, 0x2f800000, v114
	v_floor_f32_e32 v115, v115
	v_fmac_f32_e32 v114, 0xcf800000, v115
	v_cvt_u32_f32_e32 v116, v114
	v_cvt_u32_f32_e32 v117, v115
	global_atomic_add_x2 v162, v[116:117], s[8:9]
	v_mul_f32_e32 v98, 0x49800000, v98
	v_trunc_f32_e32 v98, v98
	v_mul_f32_e32 v99, 0x2f800000, v98
	v_floor_f32_e32 v99, v99
	v_fmac_f32_e32 v98, 0xcf800000, v99
	v_cvt_u32_f32_e32 v100, v98
	v_cvt_u32_f32_e32 v101, v99
	global_atomic_add_x2 v162, v[100:101], s[8:9] offset:128
	v_mul_f32_e32 v82, 0x49800000, v82
	v_trunc_f32_e32 v82, v82
	v_mul_f32_e32 v83, 0x2f800000, v82
	v_floor_f32_e32 v83, v83
	v_fmac_f32_e32 v82, 0xcf800000, v83
	v_cvt_u32_f32_e32 v84, v82
	v_cvt_u32_f32_e32 v85, v83
	global_atomic_add_x2 v162, v[84:85], s[8:9] offset:256
	v_mul_f32_e32 v66, 0x49800000, v66
	v_trunc_f32_e32 v66, v66
	v_mul_f32_e32 v67, 0x2f800000, v66
	v_floor_f32_e32 v67, v67
	v_fmac_f32_e32 v66, 0xcf800000, v67
	v_cvt_u32_f32_e32 v68, v66
	v_cvt_u32_f32_e32 v69, v67
	global_atomic_add_x2 v162, v[68:69], s[8:9] offset:384
	v_mul_f32_e32 v50, 0x49800000, v50
	v_trunc_f32_e32 v50, v50
	v_mul_f32_e32 v51, 0x2f800000, v50
	v_floor_f32_e32 v51, v51
	v_fmac_f32_e32 v50, 0xcf800000, v51
	v_cvt_u32_f32_e32 v52, v50
	v_cvt_u32_f32_e32 v53, v51
	global_atomic_add_x2 v162, v[52:53], s[8:9] offset:1024
	v_mul_f32_e32 v34, 0x49800000, v34
	v_trunc_f32_e32 v34, v34
	v_mul_f32_e32 v35, 0x2f800000, v34
	v_floor_f32_e32 v35, v35
	v_fmac_f32_e32 v34, 0xcf800000, v35
	v_cvt_u32_f32_e32 v36, v34
	v_cvt_u32_f32_e32 v37, v35
	global_atomic_add_x2 v162, v[36:37], s[8:9] offset:1152
	v_mul_f32_e32 v16, 0x49800000, v16
	v_trunc_f32_e32 v16, v16
	v_mul_f32_e32 v17, 0x2f800000, v16
	v_floor_f32_e32 v17, v17
	v_fmac_f32_e32 v16, 0xcf800000, v17
	v_cvt_u32_f32_e32 v18, v16
	v_cvt_u32_f32_e32 v19, v17
	global_atomic_add_x2 v162, v[18:19], s[8:9] offset:1280
	v_mul_f32_e32 v0, 0x49800000, v0
	v_trunc_f32_e32 v0, v0
	v_mul_f32_e32 v1, 0x2f800000, v0
	v_floor_f32_e32 v1, v1
	v_fmac_f32_e32 v0, 0xcf800000, v1
	v_cvt_u32_f32_e32 v2, v0
	v_cvt_u32_f32_e32 v3, v1
	global_atomic_add_x2 v162, v[2:3], s[8:9] offset:1408
	s_mov_b64 exec, s[42:43]
	s_movk_i32 s75, 0x80
	s_mov_b32 s76, 0x7f807f81
	s_movk_i32 s77, 0x5b
	s_branch .Lepi_done_ao

; #define PG8_BAR __builtin_amdgcn_s_barrier()
; template <class Epi, bool ALIGN_EPI = true>
; __device__ __forceinline__ void gemm_phase(PG8_LAS unsigned char* lds, const Gemm g, const StaticOrder& S, const Epi& E) {
;     ...
;         if (!has_next) break;
; #pragma unroll
;         for (int a = 0; a < 2; ++a)
; #pragma unroll
;             for (int b = 0; b < 2; ++b)
; #pragma unroll
;                 for (int m = 0; m < 4; ++m)
; #pragma unroll
;                     for (int n = 0; n < 2; ++n) acc[a][b][m][n] = (f32x4){0.f, 0.f, 0.f, 0.f};
;         cur = nxt; cA = nA; cB = nB; ++ui;
;         if constexpr (ALIGN_EPI) { if (wr == 1) PG8_BAR; }
.Lepi_done_ao:
	s_andn2_b64 vcc, exec, s[4:5]
	s_mov_b64 s[4:5], -1
	s_cbranch_vccnz .LBB0_791
	s_andn2_b64 vcc, exec, s[18:19]
	s_cbranch_vccnz .LBB0_790
	s_barrier
	s_branch .LBB0_790
